# compressed pass 2: four neighbour-column importance updates batched (reads together, then adds, then writes); item start: importance clear straight-line instead of a 33-trip exec-mask loop
# speedup vs baseline: 1.0959x; 1.0031x over previous
; DI void nsa_item(int wv0, PP p, int item, unsigned char* smem) {
;     ...
;   for (int e = tid; e < 2 * 64 * 132; e += NT_) sImp0[e] = 0.f;
.LBB0_793:
	v_mov_b32_e32 v26, v137
	s_movk_i32 s2, 0x4200
	s_nop 0
	v_cmp_gt_i32_e32 vcc, s2, v26
	s_and_saveexec_b64 s[2:3], vcc
	s_cbranch_execz .LBB0_796
	s_add_i32 s4, 32, 0xd800
	v_lshl_add_u32 v0, v26, 2, s4
	v_add_u32_e32 v2, 0x8000, v0
	ds_write_b32 v0, v1
	ds_write_b32 v0, v1 offset:2048
	ds_write_b32 v0, v1 offset:4096
	ds_write_b32 v0, v1 offset:6144
	ds_write_b32 v0, v1 offset:8192
	ds_write_b32 v0, v1 offset:10240
	ds_write_b32 v0, v1 offset:12288
	ds_write_b32 v0, v1 offset:14336
	ds_write_b32 v0, v1 offset:16384
	ds_write_b32 v0, v1 offset:18432
	ds_write_b32 v0, v1 offset:20480
	ds_write_b32 v0, v1 offset:22528
	ds_write_b32 v0, v1 offset:24576
	ds_write_b32 v0, v1 offset:26624
	ds_write_b32 v0, v1 offset:28672
	ds_write_b32 v0, v1 offset:30720
	ds_write_b32 v2, v1
	ds_write_b32 v2, v1 offset:2048
	ds_write_b32 v2, v1 offset:4096
	ds_write_b32 v2, v1 offset:6144
	ds_write_b32 v2, v1 offset:8192
	ds_write_b32 v2, v1 offset:10240
	ds_write_b32 v2, v1 offset:12288
	ds_write_b32 v2, v1 offset:14336
	ds_write_b32 v2, v1 offset:16384
	ds_write_b32 v2, v1 offset:18432
	ds_write_b32 v2, v1 offset:20480
	ds_write_b32 v2, v1 offset:22528
	ds_write_b32 v2, v1 offset:24576
	ds_write_b32 v2, v1 offset:26624
	ds_write_b32 v2, v1 offset:28672
	ds_write_b32 v2, v1 offset:30720
	ds_write_b32 v2, v1 offset:32768

; DI f32x4 mfma16(bf16x8 a, bf16x8 b, f32x4 c) { return __builtin_amdgcn_mfma_f32_16x16x32_bf16(a, b, c, 0, 0, 0); }
; template <int MODE, bool MASKED, class MaskF>
; DI void flash_tile(const u16* sK, const u16* sV, const bf16x8 (&qf)[2][2], f32x4 (&O)[2][4], float (&m)[2], float (&l)[2],
;                    float (&ps)[4][4], MaskF ok, bool sel, int lane) {
;     ...
;     for (int ks = 0; ks < 2; ++ks) kf[kt][ks] = *(const bf16x8*)(sK + (16 * kt + l15) * 72 + ks * 32 + lg * 8);
;   if (MODE == 1) {
; #pragma unroll
;     for (int a = 0; a < 4; ++a)
; #pragma unroll
;       for (int b = 0; b < 4; ++b) ps[a][b] = 0.f;
;   }
;   union PFrag { unsigned u[4]; bf16x8 v; };
;   PFrag pf[2][2];
; #pragma unroll
;   for (int qt = 0; qt < 2; ++qt) {
;     f32x4 s[4];
;     const float sinit = (MODE == 3) ? ((MASKED || sel) ? m[qt] : -1e30f) : 0.f;
; #pragma unroll
;     for (int kt = 0; kt < 4; ++kt) {
;       s[kt] = f32x4{sinit, sinit, sinit, sinit};
; #pragma unroll
;       for (int ks = 0; ks < 2; ++ks) s[kt] = mfma16(kf[kt][ks], qf[qt][ks], s[kt]);
;     }
;     float pr[4][4];
;     if (MODE == 3) {
;       float rs = 0.f;
; #pragma unroll
;       for (int kt = 0; kt < 4; ++kt)
; #pragma unroll
;         for (int i = 0; i < 4; ++i) {
;           float pv = __builtin_amdgcn_exp2f(s[kt][i]);
;           if (MASKED) pv = ok(kt, i) ? pv : 0.f;
;           pr[kt][i] = pv;
;           rs += pv;
;         }
;       l[qt] += rs;
;     } else {
;     float mx = -1e30f;
; #pragma unroll
;     for (int kt = 0; kt < 4; ++kt)
; #pragma unroll
;       for (int i = 0; i < 4; ++i) {
;         if (MASKED) s[kt][i] = ok(kt, i) ? s[kt][i] : -1e30f;
;         mx = fmaxf(mx, s[kt][i]);
;       }
;     if (!MASKED) mx = sel ? mx : -1e30f;
;     if (MODE == 1) {
;       const float mm = m[qt], il = l[qt];
; #pragma unroll
;       for (int kt = 0; kt < 4; ++kt)
; #pragma unroll
;         for (int i = 0; i < 4; ++i) {
;           const float pv = (s[kt][i] > -1e29f) ? __builtin_amdgcn_exp2f(s[kt][i] - mm) * il : 0.f;
;           pr[kt][i] = pv;
;           ps[kt][i] += pv;
;         }
.LBB0_805:
	ds_read_b128 v[58:61], v78
	ds_read_b128 v[88:91], v78 offset:64
	v_add_u32_e32 v87, 0xfffffcd0, v77
	ds_read_b128 v[96:99], v78 offset:2304
	ds_read_b128 v[100:103], v78 offset:2368
	ds_read_b128 v[108:111], v78 offset:4608
	ds_read_b128 v[112:115], v78 offset:4672
	s_waitcnt lgkmcnt(5)
	v_mfma_f32_16x16x32_bf16 v[92:95], v[58:61], v[2:5], 0
	ds_read_b128 v[116:119], v79
	ds_read_b128 v[120:123], v79 offset:64
	v_cmp_gt_i32_e32 vcc, v87, v151
	v_add_u32_e32 v124, 0xfffffce0, v77
	s_waitcnt lgkmcnt(6)
	v_mfma_f32_16x16x32_bf16 v[92:95], v[88:91], v[6:9], v[92:95]
	v_cmp_gt_i32_e64 s[2:3], v124, v151
	v_add_u32_e32 v131, 0xfffffdd0, v77
	v_cmp_gt_i32_e64 s[8:9], v131, v151
	v_add_u32_e32 v131, 0xfffffde0, v77
	v_cmp_gt_i32_e64 s[10:11], v131, v151
	s_nop 2
	v_cndmask_b32_e32 v87, v92, v148, vcc
	v_add_u32_e32 v92, 0xfffffcf0, v77
	v_cmp_gt_i32_e64 s[4:5], v92, v151
	v_add_u32_e32 v92, 0xfffffd00, v77
	v_cmp_gt_i32_e64 s[6:7], v92, v151
	v_cndmask_b32_e64 v128, v93, v148, s[2:3]
	v_cndmask_b32_e64 v129, v94, v148, s[4:5]
	v_cndmask_b32_e64 v130, v95, v148, s[6:7]
	s_waitcnt lgkmcnt(1)
	v_mfma_f32_16x16x32_bf16 v[92:95], v[116:119], v[2:5], 0
	v_add_u32_e32 v131, 0xfffffdf0, v77
	v_cmp_gt_i32_e64 s[12:13], v131, v151
	v_add_u32_e32 v131, 0xfffffe00, v77
	s_waitcnt lgkmcnt(0)
	v_mfma_f32_16x16x32_bf16 v[92:95], v[120:123], v[6:9], v[92:95]
	v_cmp_gt_i32_e64 s[14:15], v131, v151
	v_add_u32_e32 v131, 0xfffffed0, v77
	v_cmp_gt_i32_e64 s[16:17], v131, v151
	v_add_u32_e32 v131, 0xfffffee0, v77
	v_cmp_gt_i32_e64 s[18:19], v131, v151
	v_add_u32_e32 v131, 0xfffffef0, v77
	v_cmp_gt_i32_e64 s[20:21], v131, v151
	v_add_u32_e32 v131, 0xffffff00, v77
	v_sub_f32_e32 v132, v87, v80
	v_cmp_gt_i32_e64 s[30:31], v77, v151
	v_cmp_gt_i32_e64 s[22:23], v131, v151
	v_subrev_u32_e32 v131, 48, v77
	v_exp_f32_e32 v132, v132
	v_cndmask_b32_e64 v133, v95, v148, s[30:31]
	v_sub_f32_e32 v95, v128, v80
	v_cmp_gt_i32_e64 s[24:25], v131, v151
	v_subrev_u32_e32 v131, 32, v77
	v_exp_f32_e32 v95, v95
	v_cmp_gt_i32_e64 s[26:27], v131, v151
	v_add_u32_e32 v131, -16, v77
	v_cmp_gt_i32_e64 s[28:29], v131, v151
	v_cmp_lt_f32_e64 s[34:35], s82, v87
	v_mfma_f32_16x16x32_bf16 v[104:107], v[96:99], v[2:5], 0
	v_cndmask_b32_e64 v131, v94, v148, s[28:29]
	v_mul_f32_e32 v94, v82, v132
	v_cndmask_b32_e64 v87, 0, v94, s[34:35]
	v_mul_f32_e32 v94, v82, v95
	v_sub_f32_e32 v95, v129, v80
	v_exp_f32_e32 v95, v95
	v_cmp_lt_f32_e64 s[34:35], s82, v128
	v_mfma_f32_16x16x32_bf16 v[104:107], v[100:103], v[6:9], v[104:107]
	v_cndmask_b32_e64 v92, v92, v148, s[24:25]
	v_cndmask_b32_e64 v128, 0, v94, s[34:35]
	v_mul_f32_e32 v94, v82, v95
	v_sub_f32_e32 v95, v130, v80
	v_exp_f32_e32 v95, v95
	s_nop 2
	v_cndmask_b32_e64 v104, v104, v148, s[8:9]
	v_cmp_lt_f32_e64 s[34:35], s82, v129
	v_cndmask_b32_e64 v105, v105, v148, s[10:11]
	v_cndmask_b32_e64 v106, v106, v148, s[12:13]
	v_cndmask_b32_e64 v129, 0, v94, s[34:35]
	v_mul_f32_e32 v94, v82, v95
	v_sub_f32_e32 v95, v104, v80
	v_exp_f32_e32 v95, v95
	v_cmp_lt_f32_e64 s[34:35], s82, v130
	v_mfma_f32_16x16x32_bf16 v[124:127], v[108:111], v[2:5], 0
	v_cndmask_b32_e64 v107, v107, v148, s[14:15]
	v_cndmask_b32_e64 v130, 0, v94, s[34:35]
	v_mul_f32_e32 v94, v82, v95
	v_sub_f32_e32 v95, v105, v80
	v_exp_f32_e32 v95, v95
	v_cmp_lt_f32_e64 s[34:35], s82, v104
	v_mfma_f32_16x16x32_bf16 v[124:127], v[112:115], v[6:9], v[124:127]
	v_cndmask_b32_e64 v93, v93, v148, s[26:27]
	v_cndmask_b32_e64 v104, 0, v94, s[34:35]
	v_mul_f32_e32 v94, v82, v95
	v_sub_f32_e32 v95, v106, v80
	v_exp_f32_e32 v95, v95
	v_cmp_lt_f32_e64 s[34:35], s82, v105
	s_nop 1
	v_cndmask_b32_e64 v124, v124, v148, s[16:17]
	v_cndmask_b32_e64 v125, v125, v148, s[18:19]
	v_cndmask_b32_e64 v105, 0, v94, s[34:35]
	v_mul_f32_e32 v94, v82, v95
	v_sub_f32_e32 v95, v107, v80
	v_exp_f32_e32 v95, v95
	v_cmp_lt_f32_e64 s[34:35], s82, v106
	v_cndmask_b32_e64 v126, v126, v148, s[20:21]
	v_cndmask_b32_e64 v127, v127, v148, s[22:23]
	v_cndmask_b32_e64 v106, 0, v94, s[34:35]
	v_mul_f32_e32 v94, v82, v95
	v_sub_f32_e32 v95, v124, v80
	v_exp_f32_e32 v95, v95
	v_cmp_lt_f32_e64 s[34:35], s82, v107
	v_mfma_f32_16x16x32_bf16 v[58:61], v[58:61], v[10:13], 0
	v_add_f32_e32 v132, 0, v87
	v_cndmask_b32_e64 v107, 0, v94, s[34:35]
	v_mul_f32_e32 v94, v82, v95
	v_sub_f32_e32 v95, v125, v80
	v_exp_f32_e32 v95, v95
	v_cmp_lt_f32_e64 s[34:35], s82, v124
	v_mfma_f32_16x16x32_bf16 v[58:61], v[88:91], v[14:17], v[58:61]
	v_add_f32_e32 v140, 0, v105
	v_cndmask_b32_e64 v124, 0, v94, s[34:35]
	v_mul_f32_e32 v94, v82, v95
	v_sub_f32_e32 v95, v126, v80
	v_exp_f32_e32 v95, v95
	v_cmp_lt_f32_e64 s[34:35], s82, v125
	v_mfma_f32_16x16x32_bf16 v[88:91], v[96:99], v[10:13], 0
	v_sub_f32_e32 v97, v133, v80
	v_cndmask_b32_e64 v125, 0, v94, s[34:35]
	v_mul_f32_e32 v94, v82, v95
	v_sub_f32_e32 v95, v127, v80
	v_exp_f32_e32 v95, v95
	v_cmp_lt_f32_e64 s[34:35], s82, v126
	v_mfma_f32_16x16x32_bf16 v[88:91], v[100:103], v[14:17], v[88:91]
	v_exp_f32_e32 v97, v97
	v_cndmask_b32_e64 v126, 0, v94, s[34:35]
	v_mul_f32_e32 v94, v82, v95
	v_sub_f32_e32 v95, v92, v80
	v_exp_f32_e32 v95, v95
	v_cmp_lt_f32_e64 s[34:35], s82, v127
	v_mul_f32_e32 v102, v82, v97
	v_cndmask_b32_e32 v103, v58, v148, vcc
	v_cndmask_b32_e64 v127, 0, v94, s[34:35]
	v_mul_f32_e32 v94, v82, v95
	v_sub_f32_e32 v95, v93, v80
	v_exp_f32_e32 v95, v95
	v_cmp_lt_f32_e64 s[34:35], s82, v92
	v_cmp_lt_f32_e32 vcc, s82, v103
	v_add_f32_e32 v141, 0, v106
	v_cndmask_b32_e64 v163, 0, v94, s[34:35]
	v_mul_f32_e32 v92, v82, v95
	v_sub_f32_e32 v94, v131, v80
	v_cmp_lt_f32_e64 s[34:35], s82, v93
	v_exp_f32_e32 v96, v94
	v_add_f32_e32 v142, 0, v107
	v_cndmask_b32_e64 v100, 0, v92, s[34:35]
; template <int MODE, bool MASKED, class MaskF>
; DI void flash_tile(const u16* sK, const u16* sV, const bf16x8 (&qf)[2][2], f32x4 (&O)[2][4], float (&m)[2], float (&l)[2],
;                    float (&ps)[4][4], MaskF ok, bool sel, int lane) {
;     ...
;           const float pv = (s[kt][i] > -1e29f) ? __builtin_amdgcn_exp2f(s[kt][i] - mm) * il : 0.f;
;           pr[kt][i] = pv;
;           ps[kt][i] += pv;
;         }
;     } else {
;       mx = fmaxf(mx, __shfl_xor(mx, 16));
;       mx = fmaxf(mx, __shfl_xor(mx, 32));
;       const float mnew = fmaxf(m[qt], mx);
;       const float alpha = __builtin_amdgcn_exp2f(m[qt] - mnew);
;       m[qt] = mnew;
;       float rs = 0.f;
;       if (MASKED) {
; #pragma unroll
;         for (int kt = 0; kt < 4; ++kt)
; #pragma unroll
;           for (int i = 0; i < 4; ++i) {
;             const float pv = (s[kt][i] > -1e29f) ? __builtin_amdgcn_exp2f(s[kt][i] - mnew) : 0.f;
;             pr[kt][i] = pv;
;             rs += pv;
;           }
;       } else {
;         const float me = sel ? mnew : 1e30f;
; #pragma unroll
;         for (int kt = 0; kt < 4; ++kt)
; #pragma unroll
;           for (int i = 0; i < 4; ++i) {
;             const float pv = __builtin_amdgcn_exp2f(s[kt][i] - me);
;             pr[kt][i] = pv;
;             rs += pv;
;           }
;       }
;       l[qt] = l[qt] * alpha + rs;
;       if (MODE == 2) {
; #pragma unroll
;         for (int dt = 0; dt < 4; ++dt) O[qt][dt] *= alpha;
;       }
;     }
;     }
;     if (MODE != 0) {
; #pragma unroll
;       for (int ks2 = 0; ks2 < 2; ++ks2) {
;         pf[qt][ks2].u[0] = pk2(pr[2 * ks2][0], pr[2 * ks2][1]);
;         pf[qt][ks2].u[1] = pk2(pr[2 * ks2][2], pr[2 * ks2][3]);
;         pf[qt][ks2].u[2] = pk2(pr[2 * ks2 + 1][0], pr[2 * ks2 + 1][1]);
;         pf[qt][ks2].u[3] = pk2(pr[2 * ks2 + 1][2], pr[2 * ks2 + 1][3]);
;       }
;     }
;   }
;   if (MODE != 0) {
; #pragma unroll
;     for (int ks2 = 0; ks2 < 2; ++ks2) {
; #pragma unroll
;       for (int dt = 0; dt < 4; ++dt) {
;         union { uint2 h[2]; bf16x8 v; } vf;
;         vf.h[0] = *(const uint2*)(sV + (16 * dt + l15) * 72 + 32 * ks2 + 4 * lg);
;         vf.h[1] = *(const uint2*)(sV + (16 * dt + l15) * 72 + 32 * ks2 + 16 + 4 * lg);
;         O[0][dt] = mfma16(vf.v, pf[0][ks2].v, O[0][dt]);
;         O[1][dt] = mfma16(vf.v, pf[1][ks2].v, O[1][dt]);
;       }
;     }
	v_mfma_f32_16x16x32_bf16 v[92:95], v[108:111], v[10:13], 0
	v_mul_f32_e32 v96, v82, v96
	v_cmp_lt_f32_e64 s[34:35], s82, v131
	v_cndmask_b32_e64 v110, v59, v148, s[2:3]
	v_mfma_f32_16x16x32_bf16 v[92:95], v[112:115], v[14:17], v[92:95]
	v_cndmask_b32_e64 v101, 0, v96, s[34:35]
	v_cndmask_b32_e64 v113, v88, v148, s[8:9]
	v_sub_f32_e32 v88, v103, v81
	v_mfma_f32_16x16x32_bf16 v[96:99], v[116:119], v[10:13], 0
	v_cndmask_b32_e64 v111, v60, v148, s[4:5]
	s_nop 2
	v_cndmask_b32_e64 v117, v95, v148, s[22:23]
	v_exp_f32_e32 v95, v88
	v_mfma_f32_16x16x32_bf16 v[96:99], v[120:123], v[14:17], v[96:99]
	v_cvt_pk_bf16_f32 v88, v87, v128
	v_cndmask_b32_e64 v112, v61, v148, s[6:7]
	v_mul_f32_e32 v87, v83, v95
	v_sub_f32_e32 v95, v110, v81
	v_exp_f32_e32 v95, v95
	s_nop 2
	v_cndmask_b32_e64 v118, v96, v148, s[24:25]
	v_sub_f32_e32 v96, v111, v81
	v_exp_f32_e32 v96, v96
	v_cndmask_b32_e32 v87, 0, v87, vcc
	v_mul_f32_e32 v95, v83, v95
	v_cmp_lt_f32_e32 vcc, s82, v110
	v_cndmask_b32_e64 v115, v90, v148, s[12:13]
	v_cvt_pk_bf16_f32 v90, v104, v105
	v_cndmask_b32_e32 v105, 0, v95, vcc
	v_mul_f32_e32 v95, v83, v96
	v_sub_f32_e32 v96, v112, v81
	v_exp_f32_e32 v96, v96
	v_cmp_lt_f32_e32 vcc, s82, v111
	v_cndmask_b32_e64 v114, v89, v148, s[10:11]
	v_cndmask_b32_e64 v116, v91, v148, s[14:15]
	v_cvt_pk_bf16_f32 v91, v106, v107
	v_cndmask_b32_e32 v106, 0, v95, vcc
	v_sub_f32_e32 v95, v113, v81
	v_mul_f32_e32 v96, v83, v96
	v_cmp_lt_f32_e32 vcc, s82, v112
	v_exp_f32_e32 v95, v95
	v_cndmask_b32_e64 v92, v92, v148, s[16:17]
	v_cndmask_b32_e32 v107, 0, v96, vcc
	v_sub_f32_e32 v96, v114, v81
	v_exp_f32_e32 v96, v96
	v_mul_f32_e32 v95, v83, v95
	v_cmp_lt_f32_e32 vcc, s82, v113
	v_cndmask_b32_e64 v93, v93, v148, s[18:19]
	v_mul_f32_e32 v96, v83, v96
	v_cndmask_b32_e32 v110, 0, v95, vcc
	v_sub_f32_e32 v95, v115, v81
	v_cmp_lt_f32_e32 vcc, s82, v114
	v_exp_f32_e32 v95, v95
	v_cndmask_b32_e64 v94, v94, v148, s[20:21]
	v_cndmask_b32_e32 v111, 0, v96, vcc
	v_sub_f32_e32 v96, v116, v81
	v_exp_f32_e32 v96, v96
	v_mul_f32_e32 v95, v83, v95
	v_cmp_lt_f32_e32 vcc, s82, v115
	v_cmp_lt_f32_e64 s[34:35], s82, v133
	v_mul_f32_e32 v96, v83, v96
	v_cndmask_b32_e32 v112, 0, v95, vcc
	v_sub_f32_e32 v95, v92, v81
	v_cmp_lt_f32_e32 vcc, s82, v116
	v_exp_f32_e32 v95, v95
	v_add_f32_e32 v139, 0, v104
	v_cndmask_b32_e32 v113, 0, v96, vcc
	v_sub_f32_e32 v96, v93, v81
	v_exp_f32_e32 v96, v96
	v_cmp_lt_f32_e32 vcc, s82, v92
	v_sub_f32_e32 v92, v94, v81
	v_exp_f32_e32 v92, v92
	v_mul_f32_e32 v95, v83, v95
	v_cndmask_b32_e32 v114, 0, v95, vcc
	v_mul_f32_e32 v95, v83, v96
	v_cmp_lt_f32_e32 vcc, s82, v93
	v_mul_f32_e32 v92, v83, v92
	v_cndmask_b32_e64 v102, 0, v102, s[34:35]
	v_cndmask_b32_e32 v115, 0, v95, vcc
	v_cmp_lt_f32_e32 vcc, s82, v94
	v_add_f32_e32 v104, v132, v87
	v_add_u32_e32 v122, 0x2000, v84
	v_cndmask_b32_e32 v116, 0, v92, vcc
	v_sub_f32_e32 v92, v117, v81
	v_exp_f32_e32 v96, v92
	v_cmp_lt_f32_e32 vcc, s82, v117
	v_sub_f32_e32 v92, v118, v81
	v_add_f32_e32 v165, 0, v100
	v_mul_f32_e32 v96, v83, v96
	v_cndmask_b32_e32 v117, 0, v96, vcc
	v_cvt_pk_bf16_f32 v96, v87, v105
	v_add_u32_e32 v87, 0x2800, v84
	v_add_f32_e32 v108, 0, v101
	v_add_f32_e32 v109, 0, v102
	v_cndmask_b32_e64 v119, v97, v148, s[26:27]
	v_cvt_pk_bf16_f32 v61, v101, v102
	v_cvt_pk_bf16_f32 v60, v163, v100
	v_exp_f32_e32 v97, v92
	ds_read_b64 v[92:93], v122 offset:1024
	ds_read_b64 v[94:95], v122 offset:1056
	ds_read_b64 v[100:101], v87 offset:1280
	ds_read_b64 v[102:103], v87 offset:1312
	v_add_f32_e32 v154, 0, v125
	v_add_f32_e32 v161, 0, v126
	v_cndmask_b32_e64 v120, v98, v148, s[28:29]
	v_cndmask_b32_e64 v121, v99, v148, s[30:31]
	v_cvt_pk_bf16_f32 v58, v124, v125
	v_cvt_pk_bf16_f32 v59, v126, v127
	v_cvt_pk_bf16_f32 v89, v129, v130
	v_mul_f32_e32 v123, v83, v97
	v_cvt_pk_bf16_f32 v97, v106, v107
	v_cvt_pk_bf16_f32 v98, v110, v111
	v_cvt_pk_bf16_f32 v99, v112, v113
	v_add_u32_e32 v125, 0x3000, v84
	v_add_u32_e32 v126, 0x2000, v85
	s_waitcnt lgkmcnt(1)
	v_mfma_f32_16x16x32_bf16 v[54:57], v[92:95], v[88:91], v[54:57]
	v_add_f32_e32 v143, 0, v124
	v_sub_f32_e32 v124, v119, v81
	v_exp_f32_e32 v124, v124
	v_mfma_f32_16x16x32_bf16 v[30:33], v[92:95], v[96:99], v[30:33]
	ds_read_b64 v[92:93], v125 offset:1536
	ds_read_b64 v[94:95], v125 offset:1568
	v_cmp_lt_f32_e32 vcc, s82, v118
	v_add_f32_e32 v134, 0, v128
	s_waitcnt lgkmcnt(1)
; DI f32x4 mfma16(bf16x8 a, bf16x8 b, f32x4 c) { return __builtin_amdgcn_mfma_f32_16x16x32_bf16(a, b, c, 0, 0, 0); }
; template <int MODE, bool MASKED, class MaskF>
; DI void flash_tile(const u16* sK, const u16* sV, const bf16x8 (&qf)[2][2], f32x4 (&O)[2][4], float (&m)[2], float (&l)[2],
;                    float (&ps)[4][4], MaskF ok, bool sel, int lane) {
;     ...
;   if (MODE != 0) {
; #pragma unroll
;     for (int ks2 = 0; ks2 < 2; ++ks2) {
; #pragma unroll
;       for (int dt = 0; dt < 4; ++dt) {
;         union { uint2 h[2]; bf16x8 v; } vf;
;         vf.h[0] = *(const uint2*)(sV + (16 * dt + l15) * 72 + 32 * ks2 + 4 * lg);
;         vf.h[1] = *(const uint2*)(sV + (16 * dt + l15) * 72 + 32 * ks2 + 16 + 4 * lg);
;         O[0][dt] = mfma16(vf.v, pf[0][ks2].v, O[0][dt]);
;         O[1][dt] = mfma16(vf.v, pf[1][ks2].v, O[1][dt]);
;       }
;     }
; DI void nsa_item(int wv0, PP p, int item, unsigned char* smem) {
;     ...
; #pragma unroll
;       for (int kt = 0; kt < 4; ++kt) {
;         const int j = kb * 16 + kt * 4 + lg;
;         sImp[qloc * 132 + j] += ps[kt][0] + ps[kt][1] + ps[kt][2] + ps[kt][3];
;       }
;       __syncthreads();
; #pragma unroll
;       for (int kt = 0; kt < 4; ++kt) {
;         const int j1 = kb * 16 + kt * 4 + lg + 1;
;         if (j1 < 128) sImp[qloc * 132 + j1] += ps[kt][3];
;       }
	v_mfma_f32_16x16x32_bf16 v[50:53], v[100:103], v[88:91], v[50:53]
	v_cndmask_b32_e32 v118, 0, v123, vcc
	v_mul_f32_e32 v123, v83, v124
	v_sub_f32_e32 v124, v120, v81
	v_mfma_f32_16x16x32_bf16 v[26:29], v[100:103], v[96:99], v[26:29]
	ds_read_b64 v[100:101], v126 offset:1024
	ds_read_b64 v[102:103], v126 offset:1056
	v_exp_f32_e32 v124, v124
	v_cmp_lt_f32_e32 vcc, s82, v119
	s_waitcnt lgkmcnt(1)
	v_mfma_f32_16x16x32_bf16 v[22:25], v[92:95], v[96:99], v[22:25]
	v_add_f32_e32 v135, 0, v129
	v_cndmask_b32_e32 v119, 0, v123, vcc
	v_cmp_lt_f32_e32 vcc, s82, v120
	s_waitcnt lgkmcnt(0)
	v_mfma_f32_16x16x32_bf16 v[18:21], v[100:103], v[96:99], v[18:21]
	ds_read_b64 v[96:97], v87 offset:1344
	ds_read_b64 v[98:99], v87 offset:1376
	v_add_f32_e32 v138, 0, v130
	v_add_f32_e32 v87, v142, v113
	v_mfma_f32_16x16x32_bf16 v[46:49], v[92:95], v[88:91], v[46:49]
	v_sub_f32_e32 v93, v121, v81
	v_exp_f32_e32 v93, v93
	v_mul_f32_e32 v92, v83, v124
	v_cndmask_b32_e32 v120, 0, v92, vcc
	v_cmp_lt_f32_e32 vcc, s82, v121
	v_mul_f32_e32 v92, v83, v93
	v_cvt_pk_bf16_f32 v93, v116, v117
	v_cndmask_b32_e32 v121, 0, v92, vcc
	v_cvt_pk_bf16_f32 v92, v114, v115
	v_cvt_pk_bf16_f32 v94, v118, v119
	v_cvt_pk_bf16_f32 v95, v120, v121
	v_mfma_f32_16x16x32_bf16 v[42:45], v[100:103], v[88:91], v[42:45]
	ds_read_b64 v[88:89], v122 offset:1088
	ds_read_b64 v[90:91], v122 offset:1120
	ds_read_b64 v[100:101], v125 offset:1600
	ds_read_b64 v[102:103], v125 offset:1632
	v_add_f32_e32 v164, 0, v163
	s_waitcnt lgkmcnt(2)
	v_mfma_f32_16x16x32_bf16 v[50:53], v[96:99], v[58:61], v[50:53]
	v_add_f32_e32 v162, 0, v127
	v_cmp_gt_u32_e32 vcc, s0, v73
	v_mfma_f32_16x16x32_bf16 v[26:29], v[96:99], v[92:95], v[26:29]
	ds_read_b64 v[96:97], v126 offset:1088
	ds_read_b64 v[98:99], v126 offset:1120
	s_waitcnt lgkmcnt(2)
	v_mfma_f32_16x16x32_bf16 v[54:57], v[88:91], v[58:61], v[54:57]
	s_waitcnt lgkmcnt(1)
	v_mfma_f32_16x16x32_bf16 v[46:49], v[100:103], v[58:61], v[46:49]
	s_waitcnt lgkmcnt(0)
	v_mfma_f32_16x16x32_bf16 v[42:45], v[96:99], v[58:61], v[42:45]
	ds_read2_b32 v[60:61], v86 offset1:4
	v_add_f32_e32 v59, v108, v120
	v_add_f32_e32 v58, v109, v121
	v_mfma_f32_16x16x32_bf16 v[30:33], v[88:91], v[92:95], v[30:33]
	v_add_f32_e32 v90, v134, v105
	v_add_f32_e32 v91, v135, v106
	v_add_f32_e32 v90, v104, v90
	v_add_f32_e32 v89, v138, v107
	v_add_f32_e32 v90, v91, v90
	v_add_f32_e32 v105, v139, v110
	v_add_f32_e32 v106, v140, v111
	v_add_f32_e32 v90, v89, v90
	v_add_f32_e32 v107, v141, v112
	s_waitcnt lgkmcnt(0)
	v_add_f32_e32 v60, v90, v60
	v_add_f32_e32 v90, v105, v106
	v_add_f32_e32 v90, v107, v90
	v_mfma_f32_16x16x32_bf16 v[22:25], v[100:103], v[92:95], v[22:25]
	v_add_f32_e32 v110, v143, v114
	v_add_f32_e32 v111, v154, v115
	v_add_f32_e32 v100, v164, v118
	v_mfma_f32_16x16x32_bf16 v[18:21], v[96:99], v[92:95], v[18:21]
	v_add_f32_e32 v92, v87, v90
	ds_read2_b32 v[90:91], v86 offset0:8 offset1:12
	v_add_f32_e32 v101, v165, v119
	v_add_f32_e32 v61, v92, v61
	v_add_f32_e32 v112, v161, v116
	ds_write2_b32 v86, v60, v61 offset1:4
	v_add_f32_e32 v60, v110, v111
	v_add_f32_e32 v61, v100, v101
	v_add_f32_e32 v88, v162, v117
	v_add_f32_e32 v60, v112, v60
	v_add_f32_e32 v59, v59, v61
	v_add_f32_e32 v60, v88, v60
	v_add_f32_e32 v59, v58, v59
	s_waitcnt lgkmcnt(1)
	v_add_f32_e32 v60, v60, v90
	v_add_f32_e32 v59, v59, v91
	ds_write2_b32 v86, v60, v59 offset0:8 offset1:12
	s_waitcnt lgkmcnt(0)
	s_barrier
	s_mov_b64 s[4:5], vcc
	v_add_u32_e32 v59, 4, v73
	v_cmp_gt_u32_e64 s[6:7], s0, v59
	v_add_u32_e32 v59, 8, v73
	v_cmp_gt_u32_e64 s[8:9], s0, v59
	v_add_u32_e32 v59, 12, v73
	v_cmp_gt_u32_e64 s[10:11], s0, v59
	s_mov_b64 s[2:3], exec
	s_and_b64 exec, s[2:3], s[4:5]
	ds_read_b32 v59, v86 offset:4
	s_and_b64 exec, s[2:3], s[6:7]
	ds_read_b32 v60, v86 offset:20
	s_and_b64 exec, s[2:3], s[8:9]
	ds_read_b32 v61, v86 offset:36
	s_and_b64 exec, s[2:3], s[10:11]
	ds_read_b32 v90, v86 offset:52
	s_mov_b64 exec, s[2:3]
	s_waitcnt lgkmcnt(0)
	v_add_f32_e32 v59, v89, v59
	v_add_f32_e32 v60, v87, v60
	v_add_f32_e32 v61, v88, v61
	v_add_f32_e32 v90, v58, v90
	s_and_b64 exec, s[2:3], s[4:5]
	ds_write_b32 v86, v59 offset:4
	s_and_b64 exec, s[2:3], s[6:7]
	ds_write_b32 v86, v60 offset:20
	s_and_b64 exec, s[2:3], s[8:9]
	ds_write_b32 v86, v61 offset:36
	s_and_b64 exec, s[2:3], s[10:11]
	ds_write_b32 v86, v90 offset:52
	s_mov_b64 exec, s[2:3]
	s_branch .LBB0_802
